# work-item remap uses gridDim instead of a hardcoded 256
# baseline (speedup 1.0000x reference)
.LBB0_8:
	s_or_b64 exec, exec, s[12:13]
	s_load_dwordx16 s[36:51], s[0:1], 0x0
	s_ashr_i32 s0, s18, 6
	s_lshl_b32 s1, s2, 3
	s_mul_i32 s12, s0, s86
	s_add_i32 s12, s12, s2
	s_lshl_b32 s75, s86, 3
	s_waitcnt lgkmcnt(0)
	v_writelane_b32 v250, s36, 1
	s_cmpk_gt_i32 s12, 0x187f
	v_and_b32_e32 v1, 63, v10
	v_writelane_b32 v250, s37, 2
	v_writelane_b32 v250, s38, 3
	v_writelane_b32 v250, s39, 4
	v_writelane_b32 v250, s40, 5
	v_writelane_b32 v250, s41, 6
	v_writelane_b32 v250, s42, 7
	v_writelane_b32 v250, s43, 8
	v_writelane_b32 v250, s44, 9
	v_writelane_b32 v250, s45, 10
	v_writelane_b32 v250, s46, 11
	v_writelane_b32 v250, s47, 12
	v_writelane_b32 v250, s48, 13
	v_writelane_b32 v250, s49, 14
	v_writelane_b32 v250, s50, 15
	v_writelane_b32 v250, s51, 16
	v_writelane_b32 v250, s1, 0
	s_cbranch_scc1 .LBB0_40
	s_add_u32 s14, s84, s4
	v_and_b32_e32 v2, 7, v10
	s_addc_u32 s15, s85, s5
	s_lshl_b32 s0, s0, 14
	v_lshlrev_b32_e32 v36, 4, v2
	v_mov_b32_e32 v37, 0
	v_readlane_b32 s36, v250, 1
	s_add_i32 s6, s0, 0
	v_mul_u32_u24_e32 v5, 0x420, v2
	v_lshl_add_u64 v[2:3], s[14:15], 0, v[36:37]
	s_mov_b64 s[0:1], 0x1700000
	v_readlane_b32 s38, v250, 3
	v_lshl_add_u64 v[38:39], v[2:3], 0, s[0:1]
	v_readlane_b32 s39, v250, 4
	s_add_u32 s14, s38, 0x2000
	s_mov_b64 s[0:1], 0xc00000
	s_addc_u32 s15, s39, 0
	v_lshl_add_u64 v[40:41], v[2:3], 0, s[0:1]
	s_mov_b64 s[0:1], 0xa00000
	v_lshrrev_b32_e32 v34, 3, v1
	v_lshl_add_u64 v[42:43], v[2:3], 0, s[0:1]
	s_cmp_lg_u64 s[38:39], 0
	s_mov_b64 s[0:1], 0x400000
	v_add_u32_e32 v57, s6, v36
	v_mul_u32_u24_e32 v4, 0x84, v34
	s_cselect_b64 s[16:17], -1, 0
	v_lshl_add_u64 v[44:45], v[2:3], 0, s[0:1]
	s_lshl_b32 s0, s12, 6
	v_lshlrev_b32_e32 v6, 2, v34
	v_readlane_b32 s37, v250, 2
	v_readlane_b32 s40, v250, 5
	v_readlane_b32 s41, v250, 6
	v_readlane_b32 s44, v250, 9
	v_readlane_b32 s45, v250, 10
	v_or_b32_e32 v62, 32, v34
	s_add_i32 s23, s0, 0x7ffff800
	s_lshl_b32 s0, s12, 1
	v_add_u32_e32 v67, v57, v4
	s_mov_b32 s7, 0
	v_or_b32_e32 v58, 8, v34
	v_or_b32_e32 v59, 16, v34
	v_or_b32_e32 v60, 24, v34
	v_add3_u32 v61, s6, v5, v6
	v_mul_u32_u24_e32 v63, 0x84, v62
	v_or_b32_e32 v64, 40, v34
	v_or_b32_e32 v65, 48, v34
	v_or_b32_e32 v66, 56, v34
	v_lshl_add_u64 v[46:47], s[92:93], 0, v[36:37]
	v_lshl_add_u64 v[48:49], s[90:91], 0, v[36:37]
	v_lshl_add_u64 v[50:51], s[44:45], 0, v[36:37]
	v_lshl_add_u64 v[52:53], s[40:41], 0, v[36:37]
	v_mov_b32_e32 v35, v37
	s_lshl_b32 s13, s12, 5
	s_lshl_b32 s22, s75, 5
	s_lshl_b32 s24, s75, 6
	s_add_i32 s25, s0, 0xfffff400
	s_lshl_b32 s26, s75, 1
	v_add_u32_e32 v68, 0x420, v67
	v_add_u32_e32 v69, 0x428, v67
	v_add_u32_e32 v70, 0x840, v67
	v_add_u32_e32 v71, 0x848, v67
	v_add_u32_e32 v72, 0xc60, v67
	v_add_u32_e32 v73, 0xc68, v67
	v_add_u32_e32 v74, 0x1080, v67
	v_add_u32_e32 v75, 0x1088, v67
	v_add_u32_e32 v76, 0x14a0, v67
	v_add_u32_e32 v77, 0x14a8, v67
	v_add_u32_e32 v78, 0x18c0, v67
	v_add_u32_e32 v79, 0x18c8, v67
	v_add_u32_e32 v80, 0x1ce0, v67
	v_add_u32_e32 v81, 0x1ce8, v67
	s_movk_i32 s27, 0x7fff
	s_mov_b32 s29, 0xffff0000
	s_movk_i32 s30, 0x5800
	s_mov_b32 s31, 0x2c000
	s_mov_b32 s33, 0x58000
	s_mov_b32 s34, 0x84000
	s_mov_b32 s35, 0xb0000
	s_mov_b32 s36, 0xdc000
	s_mov_b32 s37, 0x108000
	s_mov_b32 s38, 0x134000
	s_movk_i32 s39, 0x3000
	s_mov_b32 s40, s12
	v_readlane_b32 s42, v250, 7
	v_readlane_b32 s43, v250, 8
	v_readlane_b32 s46, v250, 11
	v_readlane_b32 s47, v250, 12
	v_readlane_b32 s48, v250, 13
	v_readlane_b32 s49, v250, 14
	v_readlane_b32 s50, v250, 15
	v_readlane_b32 s51, v250, 16
	s_branch .LBB0_12

.LBB0_212:
	s_add_i32 s28, s46, 1
	s_cmp_lg_u32 s46, 3
	s_cselect_b64 s[42:43], -1, 0
	s_cmp_eq_u32 s46, 3
	s_cselect_b64 s[44:45], -1, 0
	s_and_b64 vcc, exec, s[44:45]
	s_waitcnt lgkmcnt(0)
	s_barrier
	s_cbranch_vccnz .LBB0_280
	s_ashr_i32 s8, s10, 6
	s_mul_i32 s4, s8, s86
	s_add_i32 s10, s4, s2
	s_cmp_lg_u32 s46, 0
	s_cselect_b64 s[38:39], -1, 0
	s_cmp_eq_u32 s28, 2
	s_cselect_b64 s[6:7], -1, 0
	s_and_b64 s[4:5], s[6:7], exec
	s_cselect_b32 s9, 0x400, 0
	s_cmp_eq_u32 s46, 0
	s_cselect_b64 s[4:5], -1, 0
	s_and_b64 s[12:13], s[4:5], exec
	s_cselect_b32 s11, 0, 0x200
	s_cselect_b32 s12, 0x600, s9
	s_add_i32 s13, s11, s12
	s_addk_i32 s13, 0x1280
	s_cmp_ge_i32 s10, s13
	s_cbranch_scc1 .LBB0_280
	s_mov_b32 s18, s28
	v_readlane_b32 s48, v250, 1
	s_lshl_b64 s[14:15], s[18:19], 14
	v_readlane_b32 s50, v250, 3
	v_readlane_b32 s51, v250, 4
	s_add_u32 s40, s50, s14
	s_addc_u32 s41, s51, s15
	s_lshl_b32 s8, s8, 14
	s_add_i32 s14, s8, 0
	v_readlane_b32 s8, v248, 0
	v_readlane_b32 s9, v248, 1
	s_and_b64 s[8:9], s[8:9], exec
	s_mov_b32 s8, 0x400000
	s_cselect_b32 s8, 0x1d00000, s8
	s_add_u32 s8, s16, s8
	v_and_b32_e32 v1, 7, v158
	s_addc_u32 s9, s17, 0
	v_lshlrev_b32_e32 v2, 4, v1
	v_lshl_add_u64 v[36:37], s[8:9], 0, v[2:3]
	s_mov_b64 s[8:9], 0x1300000
	v_lshl_add_u64 v[38:39], v[36:37], 0, s[8:9]
	s_add_u32 s30, s40, 0x2000
	s_mov_b64 s[8:9], 0x800000
	s_addc_u32 s31, s41, 0
	v_lshl_add_u64 v[40:41], v[36:37], 0, s[8:9]
	s_add_i32 s8, s46, -1
	s_mov_b32 s9, s19
	v_bfe_u32 v0, v158, 3, 3
	s_lshl_b64 s[16:17], s[8:9], 22
	s_ashr_i32 s9, s8, 31
	v_mul_u32_u24_e32 v1, 0x420, v1
	v_lshlrev_b32_e32 v4, 2, v0
	s_lshl_b64 s[20:21], s[18:19], 22
	s_lshl_b64 s[8:9], s[8:9], 22
	s_mul_i32 s25, s28, 0xb00000
	v_add_u32_e32 v60, s14, v2
	v_add3_u32 v65, s14, v1, v4
	s_mov_b64 s[14:15], 0x600000
	s_and_b64 s[6:7], s[6:7], exec
	s_mul_hi_u32 s24, s28, 0xb00000
	v_lshl_add_u64 v[42:43], v[36:37], 0, s[14:15]
	s_cselect_b32 s14, 0x800, 0
	s_add_u32 s6, s92, s25
	s_mul_i32 s36, s28, 0x1600000
	s_addc_u32 s7, s93, s24
	s_mul_hi_u32 s29, s28, 0x1600000
	v_lshl_add_u64 v[46:47], s[6:7], 0, v[2:3]
	s_add_u32 s6, s90, s36
	v_readlane_b32 s56, v250, 9
	s_addc_u32 s7, s91, s29
	v_readlane_b32 s57, v250, 10
	v_lshl_add_u64 v[48:49], s[6:7], 0, v[2:3]
	s_add_u32 s6, s56, s20
	s_addc_u32 s7, s57, s21
	s_add_u32 s16, s88, s16
	s_addc_u32 s17, s89, s17
	s_and_b64 s[4:5], s[4:5], exec
	v_readlane_b32 s62, v250, 15
	s_cselect_b32 s5, s7, s17
	s_cselect_b32 s4, s6, s16
	v_readlane_b32 s63, v250, 16
	v_lshl_add_u64 v[50:51], s[4:5], 0, v[2:3]
	s_add_u32 s4, s62, s8
	v_readlane_b32 s52, v250, 5
	s_mul_i32 s18, s28, 0xc00000
	s_addc_u32 s5, s63, s9
	v_readlane_b32 s53, v250, 6
	s_mul_hi_u32 s15, s28, 0xc00000
	v_lshl_add_u64 v[52:53], s[4:5], 0, v[2:3]
	s_add_u32 s4, s52, s18
	v_readlane_b32 s60, v250, 13
	v_readlane_b32 s61, v250, 14
	v_or_b32_e32 v66, 32, v0
	s_addc_u32 s5, s53, s15
	v_readlane_b32 s20, v249, 17
	v_readlane_b32 s24, v249, 19
	v_mul_u32_u24_e32 v61, 0x84, v0
	v_or_b32_e32 v62, 8, v0
	v_or_b32_e32 v63, 16, v0
	v_or_b32_e32 v64, 24, v0
	v_mul_u32_u24_e32 v67, 0x84, v66
	v_or_b32_e32 v68, 40, v0
	v_or_b32_e32 v69, 48, v0
	v_or_b32_e32 v70, 56, v0
	v_lshl_add_u64 v[44:45], s[60:61], 0, v[2:3]
	v_lshl_add_u64 v[54:55], s[4:5], 0, v[2:3]
	v_mov_b32_e32 v1, v3
	v_readlane_b32 s21, v249, 18
	v_readlane_b32 s25, v249, 20
	v_readlane_b32 s49, v250, 2
	v_readlane_b32 s54, v250, 7
	v_readlane_b32 s55, v250, 8
	v_readlane_b32 s58, v250, 11
	v_readlane_b32 s59, v250, 12
	s_branch .LBB0_217
